# in-proj gate epilogue: 1/(1+exp(-v)) by v_rcp_f32 + one Newton-Raphson step (2 FMAs) instead of the compiler-expanded 11-instruction IEEE division (f32 throughout, then the same 8-bit gate quantisatio
# speedup vs baseline: 1.0153x; 1.0107x over previous
;   template <int CAT>
;   __device__ __forceinline__ void slot(const f32x4 (&acc)[2][2][4][2], int bj, int r00, int p0, bool sunit, int fq, int c0, bf16_t* bdst, int bstride, float* fdst,
;                                        float scale) const {
;     ...
;         if (CAT == 2) {
;           unsigned q[8];
; #pragma unroll
;           for (int e = 0; e < 8; ++e) q[e] = (unsigned)(__frcp_rn(1.f + __expf(-v[e])) * 255.f + 0.5f);
;           u32x2 w8;
;           w8[0] = q[0] | (q[1] << 8) | (q[2] << 16) | (q[3] << 24);
;           w8[1] = q[4] | (q[5] << 8) | (q[6] << 16) | (q[7] << 24);
;           *(u32x2*)((unsigned char*)bdst + (size_t)r * 1024 + c0) = w8;
;           continue;
;         }
.LBB0_2489:
	s_and_b64 vcc, exec, s[0:1]
	s_cbranch_vccz .LBB0_2491
	v_mul_f32_e32 v132, 0xbfb8aa3b, v126
	v_mul_f32_e32 v133, 0xbfb8aa3b, v122
	v_exp_f32_e32 v134, v132
	v_exp_f32_e32 v135, v133
	v_mul_f32_e32 v132, 0xbfb8aa3b, v127
	v_mul_f32_e32 v133, 0xbfb8aa3b, v123
	v_exp_f32_e32 v136, v132
	v_pk_add_f32 v[134:135], v[134:135], 1.0 op_sel_hi:[1,0]
	v_exp_f32_e32 v137, v133
	v_rcp_f32_e32 v141, v135
	s_mov_b32 s2, 0x437f0000
	v_mul_f32_e32 v132, 0xbfb8aa3b, v128
	v_mul_f32_e32 v133, 0xbfb8aa3b, v124
	v_fma_f32 v142, -v135, v141, 1.0
	v_fma_f32 v135, v142, v141, v141
	v_rcp_f32_e32 v141, v134
	v_exp_f32_e32 v138, v132
	v_exp_f32_e32 v139, v133
	v_mul_f32_e32 v132, 0xbfb8aa3b, v129
	v_fma_f32 v142, -v134, v141, 1.0
	v_fma_f32 v134, v142, v141, v141
	v_pk_fma_f32 v[134:135], v[134:135], s[2:3], 0.5 op_sel_hi:[1,0,0]
	v_mul_f32_e32 v133, 0xbfb8aa3b, v125
	v_cvt_u32_f32_e32 v140, v135
	v_cvt_u32_f32_e32 v141, v134
	v_pk_add_f32 v[134:135], v[136:137], 1.0 op_sel_hi:[1,0]
	v_exp_f32_e32 v132, v132
	v_rcp_f32_e32 v137, v135
	v_exp_f32_e32 v133, v133
	v_ashrrev_i32_e32 v235, 31, v234
	v_lshl_add_u64 v[130:131], s[4:5], 0, v[234:235]
	v_fma_f32 v142, -v135, v137, 1.0
	v_fma_f32 v135, v142, v137, v137
	v_rcp_f32_e32 v137, v134
	v_pk_add_f32 v[132:133], v[132:133], 1.0 op_sel_hi:[1,0]
	v_fma_f32 v142, -v134, v137, 1.0
	v_fma_f32 v134, v142, v137, v137
	v_pk_fma_f32 v[134:135], v[134:135], s[2:3], 0.5 op_sel_hi:[1,0,0]
	s_nop 0
	v_cvt_u32_f32_e32 v136, v134
	v_cvt_u32_f32_e32 v137, v135
	v_pk_add_f32 v[134:135], v[138:139], 1.0 op_sel_hi:[1,0]
	v_lshlrev_b32_e32 v136, 8, v136
	v_rcp_f32_e32 v139, v135
	v_lshlrev_b32_e32 v137, 8, v137
	v_or_b32_e32 v137, v137, v140
	v_or_b32_e32 v136, v136, v141
	v_fma_f32 v142, -v135, v139, 1.0
	v_fma_f32 v135, v142, v139, v139
	v_rcp_f32_e32 v139, v134
	s_nop 0
	v_fma_f32 v142, -v134, v139, 1.0
	v_fma_f32 v134, v142, v139, v139
	v_rcp_f32_e32 v139, v133
	v_pk_fma_f32 v[134:135], v[134:135], s[2:3], 0.5 op_sel_hi:[1,0,0]
	v_fma_f32 v142, -v133, v139, 1.0
	v_fma_f32 v133, v142, v139, v139
	v_rcp_f32_e32 v139, v132
	v_cvt_u32_f32_sdwa v134, v134 dst_sel:WORD_1 dst_unused:UNUSED_PAD src0_sel:DWORD
	v_cvt_u32_f32_sdwa v135, v135 dst_sel:WORD_1 dst_unused:UNUSED_PAD src0_sel:DWORD
	v_fma_f32 v142, -v132, v139, 1.0
	v_fma_f32 v132, v142, v139, v139
	v_pk_fma_f32 v[132:133], v[132:133], s[2:3], 0.5 op_sel_hi:[1,0,0]
	v_or_b32_e32 v135, v137, v135
	v_cvt_u32_f32_sdwa v132, v132 dst_sel:BYTE_3 dst_unused:UNUSED_PAD src0_sel:DWORD
	v_cvt_u32_f32_sdwa v133, v133 dst_sel:BYTE_3 dst_unused:UNUSED_PAD src0_sel:DWORD
	v_or_b32_e32 v134, v136, v134
	v_or_b32_e32 v132, v134, v132
	v_or_b32_e32 v133, v135, v133
	v_lshl_add_u64 v[134:135], v[130:131], 0, v[200:201]
	global_store_dwordx2 v[134:135], v[132:133], off
	v_mul_f32_e32 v132, 0xbfb8aa3b, v118
	v_mul_f32_e32 v133, 0xbfb8aa3b, v114
	v_exp_f32_e32 v134, v132
	v_exp_f32_e32 v135, v133
	v_mul_f32_e32 v132, 0xbfb8aa3b, v119
	v_mul_f32_e32 v133, 0xbfb8aa3b, v115
	v_exp_f32_e32 v136, v132
	v_pk_add_f32 v[134:135], v[134:135], 1.0 op_sel_hi:[1,0]
	v_exp_f32_e32 v137, v133
	v_rcp_f32_e32 v141, v135
	v_mul_f32_e32 v132, 0xbfb8aa3b, v120
	v_mul_f32_e32 v133, 0xbfb8aa3b, v116
	v_exp_f32_e32 v138, v132
	v_fma_f32 v142, -v135, v141, 1.0
	v_fma_f32 v135, v142, v141, v141
	v_rcp_f32_e32 v141, v134
	v_exp_f32_e32 v139, v133
	v_mul_f32_e32 v132, 0xbfb8aa3b, v121
	v_mul_f32_e32 v133, 0xbfb8aa3b, v117
	v_fma_f32 v142, -v134, v141, 1.0
	v_fma_f32 v134, v142, v141, v141
	v_pk_fma_f32 v[134:135], v[134:135], s[2:3], 0.5 op_sel_hi:[1,0,0]
	v_exp_f32_e32 v132, v132
	v_cvt_u32_f32_e32 v140, v135
	v_cvt_u32_f32_e32 v141, v134
	v_pk_add_f32 v[134:135], v[136:137], 1.0 op_sel_hi:[1,0]
	v_exp_f32_e32 v133, v133
	v_rcp_f32_e32 v137, v135
	v_pk_add_f32 v[132:133], v[132:133], 1.0 op_sel_hi:[1,0]
	v_fma_f32 v142, -v135, v137, 1.0
	v_fma_f32 v135, v142, v137, v137
	v_rcp_f32_e32 v137, v134
	s_nop 0
	v_fma_f32 v142, -v134, v137, 1.0
	v_fma_f32 v134, v142, v137, v137
	v_pk_fma_f32 v[134:135], v[134:135], s[2:3], 0.5 op_sel_hi:[1,0,0]
	s_nop 0
	v_cvt_u32_f32_e32 v136, v134
	v_cvt_u32_f32_e32 v137, v135
	v_pk_add_f32 v[134:135], v[138:139], 1.0 op_sel_hi:[1,0]
	v_lshlrev_b32_e32 v136, 8, v136
	v_rcp_f32_e32 v139, v135
	v_lshlrev_b32_e32 v137, 8, v137
	v_or_b32_e32 v137, v137, v140
	v_or_b32_e32 v136, v136, v141
	v_fma_f32 v142, -v135, v139, 1.0
	v_fma_f32 v135, v142, v139, v139
	v_rcp_f32_e32 v139, v134
	s_nop 0
	v_fma_f32 v142, -v134, v139, 1.0
	v_fma_f32 v134, v142, v139, v139
	v_rcp_f32_e32 v139, v133
	v_pk_fma_f32 v[134:135], v[134:135], s[2:3], 0.5 op_sel_hi:[1,0,0]
	v_fma_f32 v142, -v133, v139, 1.0
	v_fma_f32 v133, v142, v139, v139
	v_rcp_f32_e32 v139, v132
	v_cvt_u32_f32_sdwa v134, v134 dst_sel:WORD_1 dst_unused:UNUSED_PAD src0_sel:DWORD
	v_cvt_u32_f32_sdwa v135, v135 dst_sel:WORD_1 dst_unused:UNUSED_PAD src0_sel:DWORD
	v_fma_f32 v142, -v132, v139, 1.0
	v_fma_f32 v132, v142, v139, v139
	v_pk_fma_f32 v[132:133], v[132:133], s[2:3], 0.5 op_sel_hi:[1,0,0]
	v_or_b32_e32 v135, v137, v135
	v_cvt_u32_f32_sdwa v132, v132 dst_sel:BYTE_3 dst_unused:UNUSED_PAD src0_sel:DWORD
	v_cvt_u32_f32_sdwa v133, v133 dst_sel:BYTE_3 dst_unused:UNUSED_PAD src0_sel:DWORD
	v_or_b32_e32 v134, v136, v134
	v_or_b32_e32 v132, v134, v132
	v_or_b32_e32 v133, v135, v133
	v_lshl_add_u64 v[134:135], v[130:131], 0, v[198:199]
	global_store_dwordx2 v[134:135], v[132:133], off
	v_mul_f32_e32 v132, 0xbfb8aa3b, v110
	v_mul_f32_e32 v133, 0xbfb8aa3b, v106
	v_exp_f32_e32 v134, v132
	v_exp_f32_e32 v135, v133
	v_mul_f32_e32 v132, 0xbfb8aa3b, v111
	v_mul_f32_e32 v133, 0xbfb8aa3b, v107
	v_exp_f32_e32 v136, v132
	v_pk_add_f32 v[134:135], v[134:135], 1.0 op_sel_hi:[1,0]
;   template <int CAT>
;   __device__ __forceinline__ void slot(const f32x4 (&acc)[2][2][4][2], int bj, int r00, int p0, bool sunit, int fq, int c0, bf16_t* bdst, int bstride, float* fdst,
;                                        float scale) const {
;     ...
;         if (CAT == 2) {
;           unsigned q[8];
; #pragma unroll
;           for (int e = 0; e < 8; ++e) q[e] = (unsigned)(__frcp_rn(1.f + __expf(-v[e])) * 255.f + 0.5f);
;           u32x2 w8;
;           w8[0] = q[0] | (q[1] << 8) | (q[2] << 16) | (q[3] << 24);
;           w8[1] = q[4] | (q[5] << 8) | (q[6] << 16) | (q[7] << 24);
;           *(u32x2*)((unsigned char*)bdst + (size_t)r * 1024 + c0) = w8;
;           continue;
;         }
	v_exp_f32_e32 v137, v133
	v_rcp_f32_e32 v141, v135
	v_mul_f32_e32 v132, 0xbfb8aa3b, v112
	v_mul_f32_e32 v133, 0xbfb8aa3b, v108
	v_exp_f32_e32 v138, v132
	v_fma_f32 v142, -v135, v141, 1.0
	v_fma_f32 v135, v142, v141, v141
	v_rcp_f32_e32 v141, v134
	v_exp_f32_e32 v139, v133
	v_mul_f32_e32 v132, 0xbfb8aa3b, v113
	v_mul_f32_e32 v133, 0xbfb8aa3b, v109
	v_fma_f32 v142, -v134, v141, 1.0
	v_fma_f32 v134, v142, v141, v141
	v_pk_fma_f32 v[134:135], v[134:135], s[2:3], 0.5 op_sel_hi:[1,0,0]
	v_exp_f32_e32 v132, v132
	v_cvt_u32_f32_e32 v140, v135
	v_cvt_u32_f32_e32 v141, v134
	v_pk_add_f32 v[134:135], v[136:137], 1.0 op_sel_hi:[1,0]
	v_exp_f32_e32 v133, v133
	v_rcp_f32_e32 v137, v135
	v_pk_add_f32 v[132:133], v[132:133], 1.0 op_sel_hi:[1,0]
	v_fma_f32 v142, -v135, v137, 1.0
	v_fma_f32 v135, v142, v137, v137
	v_rcp_f32_e32 v137, v134
	s_nop 0
	v_fma_f32 v142, -v134, v137, 1.0
	v_fma_f32 v134, v142, v137, v137
	v_pk_fma_f32 v[134:135], v[134:135], s[2:3], 0.5 op_sel_hi:[1,0,0]
	s_nop 0
	v_cvt_u32_f32_e32 v136, v134
	v_cvt_u32_f32_e32 v137, v135
	v_pk_add_f32 v[134:135], v[138:139], 1.0 op_sel_hi:[1,0]
	v_lshlrev_b32_e32 v136, 8, v136
	v_rcp_f32_e32 v139, v135
	v_lshlrev_b32_e32 v137, 8, v137
	v_or_b32_e32 v137, v137, v140
	v_or_b32_e32 v136, v136, v141
	v_fma_f32 v142, -v135, v139, 1.0
	v_fma_f32 v135, v142, v139, v139
	v_rcp_f32_e32 v139, v134
	s_nop 0
	v_fma_f32 v142, -v134, v139, 1.0
	v_fma_f32 v134, v142, v139, v139
	v_rcp_f32_e32 v139, v133
	v_pk_fma_f32 v[134:135], v[134:135], s[2:3], 0.5 op_sel_hi:[1,0,0]
	v_fma_f32 v142, -v133, v139, 1.0
	v_fma_f32 v133, v142, v139, v139
	v_rcp_f32_e32 v139, v132
	v_cvt_u32_f32_sdwa v134, v134 dst_sel:WORD_1 dst_unused:UNUSED_PAD src0_sel:DWORD
	v_cvt_u32_f32_sdwa v135, v135 dst_sel:WORD_1 dst_unused:UNUSED_PAD src0_sel:DWORD
	v_fma_f32 v142, -v132, v139, 1.0
	v_fma_f32 v132, v142, v139, v139
	v_pk_fma_f32 v[132:133], v[132:133], s[2:3], 0.5 op_sel_hi:[1,0,0]
	v_or_b32_e32 v135, v137, v135
	v_cvt_u32_f32_sdwa v132, v132 dst_sel:BYTE_3 dst_unused:UNUSED_PAD src0_sel:DWORD
	v_cvt_u32_f32_sdwa v133, v133 dst_sel:BYTE_3 dst_unused:UNUSED_PAD src0_sel:DWORD
	v_or_b32_e32 v134, v136, v134
	v_or_b32_e32 v132, v134, v132
	v_or_b32_e32 v133, v135, v133
	v_lshl_add_u64 v[134:135], v[130:131], 0, v[228:229]
	global_store_dwordx2 v[134:135], v[132:133], off
	v_mul_f32_e32 v132, 0xbfb8aa3b, v102
	v_mul_f32_e32 v133, 0xbfb8aa3b, v98
	v_exp_f32_e32 v134, v132
	v_exp_f32_e32 v135, v133
	v_mul_f32_e32 v132, 0xbfb8aa3b, v103
	v_mul_f32_e32 v133, 0xbfb8aa3b, v99
	v_exp_f32_e32 v136, v132
	v_pk_add_f32 v[134:135], v[134:135], 1.0 op_sel_hi:[1,0]
	v_exp_f32_e32 v137, v133
	v_rcp_f32_e32 v141, v135
	v_mul_f32_e32 v132, 0xbfb8aa3b, v104
	v_mul_f32_e32 v133, 0xbfb8aa3b, v100
	v_exp_f32_e32 v138, v132
	v_fma_f32 v142, -v135, v141, 1.0
	v_fma_f32 v135, v142, v141, v141
	v_rcp_f32_e32 v141, v134
	v_exp_f32_e32 v139, v133
	v_mul_f32_e32 v132, 0xbfb8aa3b, v105
	v_mul_f32_e32 v133, 0xbfb8aa3b, v101
	v_fma_f32 v142, -v134, v141, 1.0
	v_fma_f32 v134, v142, v141, v141
	v_pk_fma_f32 v[134:135], v[134:135], s[2:3], 0.5 op_sel_hi:[1,0,0]
	v_exp_f32_e32 v132, v132
	v_cvt_u32_f32_e32 v140, v135
	v_cvt_u32_f32_e32 v141, v134
	v_pk_add_f32 v[134:135], v[136:137], 1.0 op_sel_hi:[1,0]
	v_exp_f32_e32 v133, v133
	v_rcp_f32_e32 v137, v135
	v_pk_add_f32 v[132:133], v[132:133], 1.0 op_sel_hi:[1,0]
	v_fma_f32 v142, -v135, v137, 1.0
	v_fma_f32 v135, v142, v137, v137
	v_rcp_f32_e32 v137, v134
	s_nop 0
	v_fma_f32 v142, -v134, v137, 1.0
	v_fma_f32 v134, v142, v137, v137
	v_pk_fma_f32 v[134:135], v[134:135], s[2:3], 0.5 op_sel_hi:[1,0,0]
	s_nop 0
	v_cvt_u32_f32_e32 v136, v134
	v_cvt_u32_f32_e32 v137, v135
	v_pk_add_f32 v[134:135], v[138:139], 1.0 op_sel_hi:[1,0]
	v_lshlrev_b32_e32 v136, 8, v136
	v_rcp_f32_e32 v139, v135
	v_lshlrev_b32_e32 v137, 8, v137
	v_or_b32_e32 v137, v137, v140
	v_or_b32_e32 v136, v136, v141
	v_fma_f32 v142, -v135, v139, 1.0
	v_fma_f32 v135, v142, v139, v139
	v_rcp_f32_e32 v139, v134
	s_nop 0
	v_fma_f32 v142, -v134, v139, 1.0
	v_fma_f32 v134, v142, v139, v139
	v_rcp_f32_e32 v139, v133
	v_pk_fma_f32 v[134:135], v[134:135], s[2:3], 0.5 op_sel_hi:[1,0,0]
	v_fma_f32 v142, -v133, v139, 1.0
	v_fma_f32 v133, v142, v139, v139
	v_rcp_f32_e32 v139, v132
	v_cvt_u32_f32_sdwa v134, v134 dst_sel:WORD_1 dst_unused:UNUSED_PAD src0_sel:DWORD
	v_cvt_u32_f32_sdwa v135, v135 dst_sel:WORD_1 dst_unused:UNUSED_PAD src0_sel:DWORD
	v_fma_f32 v142, -v132, v139, 1.0
	v_fma_f32 v132, v142, v139, v139
	v_pk_fma_f32 v[132:133], v[132:133], s[2:3], 0.5 op_sel_hi:[1,0,0]
	v_or_b32_e32 v135, v137, v135
	v_cvt_u32_f32_sdwa v132, v132 dst_sel:BYTE_3 dst_unused:UNUSED_PAD src0_sel:DWORD
	v_cvt_u32_f32_sdwa v133, v133 dst_sel:BYTE_3 dst_unused:UNUSED_PAD src0_sel:DWORD
	v_or_b32_e32 v134, v136, v134
	v_or_b32_e32 v132, v134, v132
	v_or_b32_e32 v133, v135, v133
	v_lshl_add_u64 v[134:135], v[130:131], 0, v[242:243]
	global_store_dwordx2 v[134:135], v[132:133], off
	v_mul_f32_e32 v132, 0xbfb8aa3b, v94
	v_mul_f32_e32 v133, 0xbfb8aa3b, v90
	v_exp_f32_e32 v134, v132
	v_exp_f32_e32 v135, v133
	v_mul_f32_e32 v132, 0xbfb8aa3b, v95
	v_mul_f32_e32 v133, 0xbfb8aa3b, v91
	v_exp_f32_e32 v136, v132
	v_pk_add_f32 v[134:135], v[134:135], 1.0 op_sel_hi:[1,0]
	v_exp_f32_e32 v137, v133
	v_rcp_f32_e32 v141, v135
	v_mul_f32_e32 v132, 0xbfb8aa3b, v96
	v_mul_f32_e32 v133, 0xbfb8aa3b, v92
	v_exp_f32_e32 v138, v132
	v_fma_f32 v142, -v135, v141, 1.0
	v_fma_f32 v135, v142, v141, v141
	v_rcp_f32_e32 v141, v134
	v_exp_f32_e32 v139, v133
	v_mul_f32_e32 v132, 0xbfb8aa3b, v97
	v_mul_f32_e32 v133, 0xbfb8aa3b, v93
	v_fma_f32 v142, -v134, v141, 1.0
	v_fma_f32 v134, v142, v141, v141
;   template <int CAT>
;   __device__ __forceinline__ void slot(const f32x4 (&acc)[2][2][4][2], int bj, int r00, int p0, bool sunit, int fq, int c0, bf16_t* bdst, int bstride, float* fdst,
;                                        float scale) const {
;     ...
;         if (CAT == 2) {
;           unsigned q[8];
; #pragma unroll
;           for (int e = 0; e < 8; ++e) q[e] = (unsigned)(__frcp_rn(1.f + __expf(-v[e])) * 255.f + 0.5f);
;           u32x2 w8;
;           w8[0] = q[0] | (q[1] << 8) | (q[2] << 16) | (q[3] << 24);
;           w8[1] = q[4] | (q[5] << 8) | (q[6] << 16) | (q[7] << 24);
;           *(u32x2*)((unsigned char*)bdst + (size_t)r * 1024 + c0) = w8;
;           continue;
;         }
	v_pk_fma_f32 v[134:135], v[134:135], s[2:3], 0.5 op_sel_hi:[1,0,0]
	v_exp_f32_e32 v132, v132
	v_cvt_u32_f32_e32 v140, v135
	v_cvt_u32_f32_e32 v141, v134
	v_pk_add_f32 v[134:135], v[136:137], 1.0 op_sel_hi:[1,0]
	v_exp_f32_e32 v133, v133
	v_rcp_f32_e32 v137, v135
	v_pk_add_f32 v[132:133], v[132:133], 1.0 op_sel_hi:[1,0]
	v_fma_f32 v142, -v135, v137, 1.0
	v_fma_f32 v135, v142, v137, v137
	v_rcp_f32_e32 v137, v134
	s_nop 0
	v_fma_f32 v142, -v134, v137, 1.0
	v_fma_f32 v134, v142, v137, v137
	v_pk_fma_f32 v[134:135], v[134:135], s[2:3], 0.5 op_sel_hi:[1,0,0]
	s_nop 0
	v_cvt_u32_f32_e32 v136, v134
	v_cvt_u32_f32_e32 v137, v135
	v_pk_add_f32 v[134:135], v[138:139], 1.0 op_sel_hi:[1,0]
	v_lshlrev_b32_e32 v136, 8, v136
	v_rcp_f32_e32 v139, v135
	v_lshlrev_b32_e32 v137, 8, v137
	v_or_b32_e32 v137, v137, v140
	v_or_b32_e32 v136, v136, v141
	v_fma_f32 v142, -v135, v139, 1.0
	v_fma_f32 v135, v142, v139, v139
	v_rcp_f32_e32 v139, v134
	s_nop 0
	v_fma_f32 v142, -v134, v139, 1.0
	v_fma_f32 v134, v142, v139, v139
	v_rcp_f32_e32 v139, v133
	v_pk_fma_f32 v[134:135], v[134:135], s[2:3], 0.5 op_sel_hi:[1,0,0]
	v_fma_f32 v142, -v133, v139, 1.0
	v_fma_f32 v133, v142, v139, v139
	v_rcp_f32_e32 v139, v132
	v_cvt_u32_f32_sdwa v134, v134 dst_sel:WORD_1 dst_unused:UNUSED_PAD src0_sel:DWORD
	v_cvt_u32_f32_sdwa v135, v135 dst_sel:WORD_1 dst_unused:UNUSED_PAD src0_sel:DWORD
	v_fma_f32 v142, -v132, v139, 1.0
	v_fma_f32 v132, v142, v139, v139
	v_pk_fma_f32 v[132:133], v[132:133], s[2:3], 0.5 op_sel_hi:[1,0,0]
	v_or_b32_e32 v135, v137, v135
	v_cvt_u32_f32_sdwa v132, v132 dst_sel:BYTE_3 dst_unused:UNUSED_PAD src0_sel:DWORD
	v_cvt_u32_f32_sdwa v133, v133 dst_sel:BYTE_3 dst_unused:UNUSED_PAD src0_sel:DWORD
	v_or_b32_e32 v134, v136, v134
	v_or_b32_e32 v132, v134, v132
	v_or_b32_e32 v133, v135, v133
	v_lshl_add_u64 v[134:135], v[130:131], 0, v[224:225]
	global_store_dwordx2 v[134:135], v[132:133], off
	v_mul_f32_e32 v132, 0xbfb8aa3b, v86
	v_mul_f32_e32 v133, 0xbfb8aa3b, v82
	v_exp_f32_e32 v134, v132
	v_exp_f32_e32 v135, v133
	v_mul_f32_e32 v132, 0xbfb8aa3b, v87
	v_mul_f32_e32 v133, 0xbfb8aa3b, v83
	v_exp_f32_e32 v136, v132
	v_pk_add_f32 v[134:135], v[134:135], 1.0 op_sel_hi:[1,0]
	v_exp_f32_e32 v137, v133
	v_rcp_f32_e32 v141, v135
	v_mul_f32_e32 v132, 0xbfb8aa3b, v88
	v_mul_f32_e32 v133, 0xbfb8aa3b, v84
	v_exp_f32_e32 v138, v132
	v_fma_f32 v142, -v135, v141, 1.0
	v_fma_f32 v135, v142, v141, v141
	v_rcp_f32_e32 v141, v134
	v_exp_f32_e32 v139, v133
	v_mul_f32_e32 v132, 0xbfb8aa3b, v89
	v_mul_f32_e32 v133, 0xbfb8aa3b, v85
	v_fma_f32 v142, -v134, v141, 1.0
	v_fma_f32 v134, v142, v141, v141
	v_pk_fma_f32 v[134:135], v[134:135], s[2:3], 0.5 op_sel_hi:[1,0,0]
	v_exp_f32_e32 v132, v132
	v_cvt_u32_f32_e32 v140, v135
	v_cvt_u32_f32_e32 v141, v134
	v_pk_add_f32 v[134:135], v[136:137], 1.0 op_sel_hi:[1,0]
	v_exp_f32_e32 v133, v133
	v_rcp_f32_e32 v137, v135
	v_pk_add_f32 v[132:133], v[132:133], 1.0 op_sel_hi:[1,0]
	v_fma_f32 v142, -v135, v137, 1.0
	v_fma_f32 v135, v142, v137, v137
	v_rcp_f32_e32 v137, v134
	s_nop 0
	v_fma_f32 v142, -v134, v137, 1.0
	v_fma_f32 v134, v142, v137, v137
	v_pk_fma_f32 v[134:135], v[134:135], s[2:3], 0.5 op_sel_hi:[1,0,0]
	s_nop 0
	v_cvt_u32_f32_e32 v136, v134
	v_cvt_u32_f32_e32 v137, v135
	v_pk_add_f32 v[134:135], v[138:139], 1.0 op_sel_hi:[1,0]
	v_lshlrev_b32_e32 v136, 8, v136
	v_rcp_f32_e32 v139, v135
	v_lshlrev_b32_e32 v137, 8, v137
	v_or_b32_e32 v137, v137, v140
	v_or_b32_e32 v136, v136, v141
	v_fma_f32 v142, -v135, v139, 1.0
	v_fma_f32 v135, v142, v139, v139
	v_rcp_f32_e32 v139, v134
	s_nop 0
	v_fma_f32 v142, -v134, v139, 1.0
	v_fma_f32 v134, v142, v139, v139
	v_rcp_f32_e32 v139, v133
	v_pk_fma_f32 v[134:135], v[134:135], s[2:3], 0.5 op_sel_hi:[1,0,0]
	v_fma_f32 v142, -v133, v139, 1.0
	v_fma_f32 v133, v142, v139, v139
	v_rcp_f32_e32 v139, v132
	v_cvt_u32_f32_sdwa v134, v134 dst_sel:WORD_1 dst_unused:UNUSED_PAD src0_sel:DWORD
	v_cvt_u32_f32_sdwa v135, v135 dst_sel:WORD_1 dst_unused:UNUSED_PAD src0_sel:DWORD
	v_fma_f32 v142, -v132, v139, 1.0
	v_fma_f32 v132, v142, v139, v139
	v_pk_fma_f32 v[132:133], v[132:133], s[2:3], 0.5 op_sel_hi:[1,0,0]
	v_or_b32_e32 v135, v137, v135
	v_cvt_u32_f32_sdwa v132, v132 dst_sel:BYTE_3 dst_unused:UNUSED_PAD src0_sel:DWORD
	v_cvt_u32_f32_sdwa v133, v133 dst_sel:BYTE_3 dst_unused:UNUSED_PAD src0_sel:DWORD
	v_or_b32_e32 v134, v136, v134
	v_or_b32_e32 v132, v134, v132
	v_or_b32_e32 v133, v135, v133
	v_lshl_add_u64 v[134:135], v[130:131], 0, v[222:223]
	global_store_dwordx2 v[134:135], v[132:133], off
	v_mul_f32_e32 v132, 0xbfb8aa3b, v78
	v_mul_f32_e32 v133, 0xbfb8aa3b, v74
	v_exp_f32_e32 v134, v132
	v_exp_f32_e32 v135, v133
	v_mul_f32_e32 v132, 0xbfb8aa3b, v79
	v_mul_f32_e32 v133, 0xbfb8aa3b, v75
	v_exp_f32_e32 v136, v132
	v_pk_add_f32 v[134:135], v[134:135], 1.0 op_sel_hi:[1,0]
	v_exp_f32_e32 v137, v133
	v_rcp_f32_e32 v141, v135
	v_mul_f32_e32 v132, 0xbfb8aa3b, v80
;   template <int CAT>
;   __device__ __forceinline__ void slot(const f32x4 (&acc)[2][2][4][2], int bj, int r00, int p0, bool sunit, int fq, int c0, bf16_t* bdst, int bstride, float* fdst,
;                                        float scale) const {
;     ...
;         if (CAT == 2) {
;           unsigned q[8];
; #pragma unroll
;           for (int e = 0; e < 8; ++e) q[e] = (unsigned)(__frcp_rn(1.f + __expf(-v[e])) * 255.f + 0.5f);
;           u32x2 w8;
;           w8[0] = q[0] | (q[1] << 8) | (q[2] << 16) | (q[3] << 24);
;           w8[1] = q[4] | (q[5] << 8) | (q[6] << 16) | (q[7] << 24);
;           *(u32x2*)((unsigned char*)bdst + (size_t)r * 1024 + c0) = w8;
;           continue;
	v_mul_f32_e32 v133, 0xbfb8aa3b, v76
	v_exp_f32_e32 v138, v132
	v_fma_f32 v142, -v135, v141, 1.0
	v_fma_f32 v135, v142, v141, v141
	v_rcp_f32_e32 v141, v134
	v_exp_f32_e32 v139, v133
	v_mul_f32_e32 v132, 0xbfb8aa3b, v81
	v_mul_f32_e32 v133, 0xbfb8aa3b, v77
	v_fma_f32 v142, -v134, v141, 1.0
	v_fma_f32 v134, v142, v141, v141
	v_pk_fma_f32 v[134:135], v[134:135], s[2:3], 0.5 op_sel_hi:[1,0,0]
	v_exp_f32_e32 v132, v132
	v_cvt_u32_f32_e32 v140, v135
	v_cvt_u32_f32_e32 v141, v134
	v_pk_add_f32 v[134:135], v[136:137], 1.0 op_sel_hi:[1,0]
	v_exp_f32_e32 v133, v133
	v_rcp_f32_e32 v137, v135
	v_pk_add_f32 v[132:133], v[132:133], 1.0 op_sel_hi:[1,0]
	v_fma_f32 v142, -v135, v137, 1.0
	v_fma_f32 v135, v142, v137, v137
	v_rcp_f32_e32 v137, v134
	s_nop 0
	v_fma_f32 v142, -v134, v137, 1.0
	v_fma_f32 v134, v142, v137, v137
	v_pk_fma_f32 v[134:135], v[134:135], s[2:3], 0.5 op_sel_hi:[1,0,0]
	s_nop 0
	v_cvt_u32_f32_e32 v136, v134
	v_cvt_u32_f32_e32 v137, v135
	v_pk_add_f32 v[134:135], v[138:139], 1.0 op_sel_hi:[1,0]
	v_lshlrev_b32_e32 v136, 8, v136
	v_rcp_f32_e32 v139, v135
	v_lshlrev_b32_e32 v137, 8, v137
	v_or_b32_e32 v137, v137, v140
	v_or_b32_e32 v136, v136, v141
	v_fma_f32 v142, -v135, v139, 1.0
	v_fma_f32 v135, v142, v139, v139
	v_rcp_f32_e32 v139, v134
	s_nop 0
	v_fma_f32 v142, -v134, v139, 1.0
	v_fma_f32 v134, v142, v139, v139
	v_rcp_f32_e32 v139, v133
	v_pk_fma_f32 v[134:135], v[134:135], s[2:3], 0.5 op_sel_hi:[1,0,0]
	v_fma_f32 v142, -v133, v139, 1.0
	v_fma_f32 v133, v142, v139, v139
	v_rcp_f32_e32 v139, v132
	v_cvt_u32_f32_sdwa v134, v134 dst_sel:WORD_1 dst_unused:UNUSED_PAD src0_sel:DWORD
	v_cvt_u32_f32_sdwa v135, v135 dst_sel:WORD_1 dst_unused:UNUSED_PAD src0_sel:DWORD
	v_fma_f32 v142, -v132, v139, 1.0
	v_fma_f32 v132, v142, v139, v139
	v_pk_fma_f32 v[132:133], v[132:133], s[2:3], 0.5 op_sel_hi:[1,0,0]
	v_or_b32_e32 v135, v137, v135
	v_cvt_u32_f32_sdwa v132, v132 dst_sel:BYTE_3 dst_unused:UNUSED_PAD src0_sel:DWORD
	v_cvt_u32_f32_sdwa v133, v133 dst_sel:BYTE_3 dst_unused:UNUSED_PAD src0_sel:DWORD
	v_or_b32_e32 v134, v136, v134
	v_or_b32_e32 v132, v134, v132
	v_or_b32_e32 v133, v135, v133
	v_lshl_add_u64 v[134:135], v[130:131], 0, v[148:149]
	global_store_dwordx2 v[134:135], v[132:133], off
	v_mul_f32_e32 v132, 0xbfb8aa3b, v70
	v_mul_f32_e32 v133, 0xbfb8aa3b, v66
	v_exp_f32_e32 v134, v132
	v_exp_f32_e32 v135, v133
	v_mul_f32_e32 v132, 0xbfb8aa3b, v71
	v_mul_f32_e32 v133, 0xbfb8aa3b, v67
	v_exp_f32_e32 v136, v132
	v_pk_add_f32 v[134:135], v[134:135], 1.0 op_sel_hi:[1,0]
	v_exp_f32_e32 v137, v133
	v_rcp_f32_e32 v141, v135
	v_mul_f32_e32 v132, 0xbfb8aa3b, v72
	v_mul_f32_e32 v133, 0xbfb8aa3b, v68
	v_exp_f32_e32 v138, v132
	v_fma_f32 v142, -v135, v141, 1.0
	v_fma_f32 v135, v142, v141, v141
	v_rcp_f32_e32 v141, v134
	v_exp_f32_e32 v139, v133
	v_mul_f32_e32 v132, 0xbfb8aa3b, v73
	v_mul_f32_e32 v133, 0xbfb8aa3b, v69
	v_fma_f32 v142, -v134, v141, 1.0
	v_fma_f32 v134, v142, v141, v141
	v_pk_fma_f32 v[134:135], v[134:135], s[2:3], 0.5 op_sel_hi:[1,0,0]
	v_exp_f32_e32 v132, v132
	v_cvt_u32_f32_e32 v140, v135
	v_cvt_u32_f32_e32 v141, v134
	v_pk_add_f32 v[134:135], v[136:137], 1.0 op_sel_hi:[1,0]
	v_exp_f32_e32 v133, v133
	v_rcp_f32_e32 v137, v135
	v_pk_add_f32 v[132:133], v[132:133], 1.0 op_sel_hi:[1,0]
	v_lshl_add_u64 v[130:131], v[130:131], 0, v[146:147]
	v_fma_f32 v142, -v135, v137, 1.0
	v_fma_f32 v135, v142, v137, v137
	v_rcp_f32_e32 v137, v134
	s_nop 0
	v_fma_f32 v142, -v134, v137, 1.0
	v_fma_f32 v134, v142, v137, v137
	v_pk_fma_f32 v[134:135], v[134:135], s[2:3], 0.5 op_sel_hi:[1,0,0]
	s_nop 0
	v_cvt_u32_f32_e32 v136, v134
	v_cvt_u32_f32_e32 v137, v135
	v_pk_add_f32 v[134:135], v[138:139], 1.0 op_sel_hi:[1,0]
	v_lshlrev_b32_e32 v136, 8, v136
	v_rcp_f32_e32 v139, v135
	v_lshlrev_b32_e32 v137, 8, v137
	v_or_b32_e32 v137, v137, v140
	v_or_b32_e32 v136, v136, v141
	v_fma_f32 v142, -v135, v139, 1.0
	v_fma_f32 v135, v142, v139, v139
	v_rcp_f32_e32 v139, v134
	s_nop 0
	v_fma_f32 v142, -v134, v139, 1.0
	v_fma_f32 v134, v142, v139, v139
	v_rcp_f32_e32 v139, v133
	v_pk_fma_f32 v[134:135], v[134:135], s[2:3], 0.5 op_sel_hi:[1,0,0]
	v_fma_f32 v142, -v133, v139, 1.0
	v_fma_f32 v133, v142, v139, v139
	v_rcp_f32_e32 v139, v132
	v_cvt_u32_f32_sdwa v134, v134 dst_sel:WORD_1 dst_unused:UNUSED_PAD src0_sel:DWORD
	v_cvt_u32_f32_sdwa v135, v135 dst_sel:WORD_1 dst_unused:UNUSED_PAD src0_sel:DWORD
	v_fma_f32 v142, -v132, v139, 1.0
	v_fma_f32 v132, v142, v139, v139
	v_pk_fma_f32 v[132:133], v[132:133], s[2:3], 0.5 op_sel_hi:[1,0,0]
	v_or_b32_e32 v135, v137, v135
	v_cvt_u32_f32_sdwa v132, v132 dst_sel:BYTE_3 dst_unused:UNUSED_PAD src0_sel:DWORD
	v_cvt_u32_f32_sdwa v133, v133 dst_sel:BYTE_3 dst_unused:UNUSED_PAD src0_sel:DWORD
	v_or_b32_e32 v134, v136, v134
	v_lshlrev_b64 v[142:143], 4, v[172:173]
	v_lshlrev_b64 v[136:137], 4, v[174:175]
	v_or_b32_e32 v133, v135, v133
	v_or_b32_e32 v132, v134, v132
	global_store_dwordx2 v[130:131], v[132:133], off

;   template <int CAT>
;   __device__ __forceinline__ void slot(const f32x4 (&acc)[2][2][4][2], int bj, int r00, int p0, bool sunit, int fq, int c0, bf16_t* bdst, int bstride, float* fdst,
;                                        float scale) const {
;     ...
;         if (CAT == 2) {
;           unsigned q[8];
; #pragma unroll
;           for (int e = 0; e < 8; ++e) q[e] = (unsigned)(__frcp_rn(1.f + __expf(-v[e])) * 255.f + 0.5f);
;           u32x2 w8;
;           w8[0] = q[0] | (q[1] << 8) | (q[2] << 16) | (q[3] << 24);
;           w8[1] = q[4] | (q[5] << 8) | (q[6] << 16) | (q[7] << 24);
;           *(u32x2*)((unsigned char*)bdst + (size_t)r * 1024 + c0) = w8;
;           continue;
.LBB0_2668:
	s_and_b64 vcc, exec, s[0:1]
	s_cbranch_vccz .LBB0_2670
	v_mul_f32_e32 v68, 0xbfb8aa3b, v62
	v_mul_f32_e32 v69, 0xbfb8aa3b, v58
	v_exp_f32_e32 v70, v68
	v_exp_f32_e32 v71, v69
	v_mul_f32_e32 v68, 0xbfb8aa3b, v63
	v_mul_f32_e32 v69, 0xbfb8aa3b, v59
	v_exp_f32_e32 v72, v68
	v_pk_add_f32 v[70:71], v[70:71], 1.0 op_sel_hi:[1,0]
	v_exp_f32_e32 v73, v69
	v_rcp_f32_e32 v77, v71
	s_mov_b32 s2, 0x437f0000
	v_mul_f32_e32 v68, 0xbfb8aa3b, v64
	v_mul_f32_e32 v69, 0xbfb8aa3b, v60
	v_fma_f32 v78, -v71, v77, 1.0
	v_fma_f32 v71, v78, v77, v77
	v_rcp_f32_e32 v77, v70
	v_exp_f32_e32 v74, v68
	v_exp_f32_e32 v75, v69
	v_mul_f32_e32 v68, 0xbfb8aa3b, v65
	v_fma_f32 v78, -v70, v77, 1.0
	v_fma_f32 v70, v78, v77, v77
	v_pk_fma_f32 v[70:71], v[70:71], s[2:3], 0.5 op_sel_hi:[1,0,0]
	v_mul_f32_e32 v69, 0xbfb8aa3b, v61
	v_cvt_u32_f32_e32 v76, v71
	v_cvt_u32_f32_e32 v77, v70
	v_pk_add_f32 v[70:71], v[72:73], 1.0 op_sel_hi:[1,0]
	v_exp_f32_e32 v68, v68
	v_rcp_f32_e32 v73, v71
	v_exp_f32_e32 v69, v69
	v_ashrrev_i32_e32 v87, 31, v86
	v_lshl_add_u64 v[66:67], s[4:5], 0, v[86:87]
	v_fma_f32 v78, -v71, v73, 1.0
	v_fma_f32 v71, v78, v73, v73
	v_rcp_f32_e32 v73, v70
	v_pk_add_f32 v[68:69], v[68:69], 1.0 op_sel_hi:[1,0]
	v_fma_f32 v78, -v70, v73, 1.0
	v_fma_f32 v70, v78, v73, v73
	v_pk_fma_f32 v[70:71], v[70:71], s[2:3], 0.5 op_sel_hi:[1,0,0]
	s_nop 0
	v_cvt_u32_f32_e32 v72, v70
	v_cvt_u32_f32_e32 v73, v71
	v_pk_add_f32 v[70:71], v[74:75], 1.0 op_sel_hi:[1,0]
	v_lshlrev_b32_e32 v72, 8, v72
	v_rcp_f32_e32 v75, v71
	v_lshlrev_b32_e32 v73, 8, v73
	v_or_b32_e32 v73, v73, v76
	v_or_b32_e32 v72, v72, v77
	v_fma_f32 v78, -v71, v75, 1.0
	v_fma_f32 v71, v78, v75, v75
	v_rcp_f32_e32 v75, v70
	s_nop 0
	v_fma_f32 v78, -v70, v75, 1.0
	v_fma_f32 v70, v78, v75, v75
	v_rcp_f32_e32 v75, v69
	v_pk_fma_f32 v[70:71], v[70:71], s[2:3], 0.5 op_sel_hi:[1,0,0]
	v_fma_f32 v78, -v69, v75, 1.0
	v_fma_f32 v69, v78, v75, v75
	v_rcp_f32_e32 v75, v68
	v_cvt_u32_f32_sdwa v70, v70 dst_sel:WORD_1 dst_unused:UNUSED_PAD src0_sel:DWORD
	v_cvt_u32_f32_sdwa v71, v71 dst_sel:WORD_1 dst_unused:UNUSED_PAD src0_sel:DWORD
	v_fma_f32 v78, -v68, v75, 1.0
	v_fma_f32 v68, v78, v75, v75
	v_pk_fma_f32 v[68:69], v[68:69], s[2:3], 0.5 op_sel_hi:[1,0,0]
	v_or_b32_e32 v71, v73, v71
	v_cvt_u32_f32_sdwa v68, v68 dst_sel:BYTE_3 dst_unused:UNUSED_PAD src0_sel:DWORD
	v_cvt_u32_f32_sdwa v69, v69 dst_sel:BYTE_3 dst_unused:UNUSED_PAD src0_sel:DWORD
	v_or_b32_e32 v70, v72, v70
	v_or_b32_e32 v68, v70, v68
	v_or_b32_e32 v69, v71, v69
	v_lshl_add_u64 v[70:71], v[66:67], 0, v[200:201]
	global_store_dwordx2 v[70:71], v[68:69], off
	v_mul_f32_e32 v68, 0xbfb8aa3b, v54
	v_mul_f32_e32 v69, 0xbfb8aa3b, v50
	v_exp_f32_e32 v70, v68
	v_exp_f32_e32 v71, v69
	v_mul_f32_e32 v68, 0xbfb8aa3b, v55
	v_mul_f32_e32 v69, 0xbfb8aa3b, v51
	v_exp_f32_e32 v72, v68
	v_pk_add_f32 v[70:71], v[70:71], 1.0 op_sel_hi:[1,0]
	v_exp_f32_e32 v73, v69
	v_rcp_f32_e32 v77, v71
	v_mul_f32_e32 v68, 0xbfb8aa3b, v56
	v_mul_f32_e32 v69, 0xbfb8aa3b, v52
	v_exp_f32_e32 v74, v68
	v_fma_f32 v78, -v71, v77, 1.0
	v_fma_f32 v71, v78, v77, v77
	v_rcp_f32_e32 v77, v70
	v_exp_f32_e32 v75, v69
	v_mul_f32_e32 v68, 0xbfb8aa3b, v57
	v_mul_f32_e32 v69, 0xbfb8aa3b, v53
	v_fma_f32 v78, -v70, v77, 1.0
	v_fma_f32 v70, v78, v77, v77
	v_pk_fma_f32 v[70:71], v[70:71], s[2:3], 0.5 op_sel_hi:[1,0,0]
	v_exp_f32_e32 v68, v68
	v_cvt_u32_f32_e32 v76, v71
	v_cvt_u32_f32_e32 v77, v70
	v_pk_add_f32 v[70:71], v[72:73], 1.0 op_sel_hi:[1,0]
	v_exp_f32_e32 v69, v69
	v_rcp_f32_e32 v73, v71
	v_pk_add_f32 v[68:69], v[68:69], 1.0 op_sel_hi:[1,0]
	v_fma_f32 v78, -v71, v73, 1.0
	v_fma_f32 v71, v78, v73, v73
	v_rcp_f32_e32 v73, v70
	s_nop 0
	v_fma_f32 v78, -v70, v73, 1.0
	v_fma_f32 v70, v78, v73, v73
	v_pk_fma_f32 v[70:71], v[70:71], s[2:3], 0.5 op_sel_hi:[1,0,0]
	s_nop 0
	v_cvt_u32_f32_e32 v72, v70
	v_cvt_u32_f32_e32 v73, v71
	v_pk_add_f32 v[70:71], v[74:75], 1.0 op_sel_hi:[1,0]
	v_lshlrev_b32_e32 v72, 8, v72
	v_rcp_f32_e32 v75, v71
	v_lshlrev_b32_e32 v73, 8, v73
	v_or_b32_e32 v73, v73, v76
	v_or_b32_e32 v72, v72, v77
	v_fma_f32 v78, -v71, v75, 1.0
	v_fma_f32 v71, v78, v75, v75
	v_rcp_f32_e32 v75, v70
	s_nop 0
	v_fma_f32 v78, -v70, v75, 1.0
	v_fma_f32 v70, v78, v75, v75
	v_rcp_f32_e32 v75, v69
	v_pk_fma_f32 v[70:71], v[70:71], s[2:3], 0.5 op_sel_hi:[1,0,0]
	v_fma_f32 v78, -v69, v75, 1.0
	v_fma_f32 v69, v78, v75, v75
	v_rcp_f32_e32 v75, v68
	v_cvt_u32_f32_sdwa v70, v70 dst_sel:WORD_1 dst_unused:UNUSED_PAD src0_sel:DWORD
	v_cvt_u32_f32_sdwa v71, v71 dst_sel:WORD_1 dst_unused:UNUSED_PAD src0_sel:DWORD
	v_fma_f32 v78, -v68, v75, 1.0
	v_fma_f32 v68, v78, v75, v75
	v_pk_fma_f32 v[68:69], v[68:69], s[2:3], 0.5 op_sel_hi:[1,0,0]
	v_or_b32_e32 v71, v73, v71
	v_cvt_u32_f32_sdwa v68, v68 dst_sel:BYTE_3 dst_unused:UNUSED_PAD src0_sel:DWORD
	v_cvt_u32_f32_sdwa v69, v69 dst_sel:BYTE_3 dst_unused:UNUSED_PAD src0_sel:DWORD
	v_or_b32_e32 v70, v72, v70
	v_or_b32_e32 v68, v70, v68
	v_or_b32_e32 v69, v71, v69
	v_lshl_add_u64 v[70:71], v[66:67], 0, v[198:199]
	global_store_dwordx2 v[70:71], v[68:69], off
	v_mul_f32_e32 v68, 0xbfb8aa3b, v46
	v_mul_f32_e32 v69, 0xbfb8aa3b, v42
	v_exp_f32_e32 v70, v68
	v_exp_f32_e32 v71, v69
	v_mul_f32_e32 v68, 0xbfb8aa3b, v47
	v_mul_f32_e32 v69, 0xbfb8aa3b, v43
	v_exp_f32_e32 v72, v68
	v_pk_add_f32 v[70:71], v[70:71], 1.0 op_sel_hi:[1,0]
	v_exp_f32_e32 v73, v69
	v_rcp_f32_e32 v77, v71
	v_mul_f32_e32 v68, 0xbfb8aa3b, v48
	v_mul_f32_e32 v69, 0xbfb8aa3b, v44
	v_exp_f32_e32 v74, v68
	v_fma_f32 v78, -v71, v77, 1.0
	v_fma_f32 v71, v78, v77, v77
	v_rcp_f32_e32 v77, v70
	v_exp_f32_e32 v75, v69
	v_mul_f32_e32 v68, 0xbfb8aa3b, v49
	v_mul_f32_e32 v69, 0xbfb8aa3b, v45
	v_fma_f32 v78, -v70, v77, 1.0
;   template <int CAT>
;   __device__ __forceinline__ void slot(const f32x4 (&acc)[2][2][4][2], int bj, int r00, int p0, bool sunit, int fq, int c0, bf16_t* bdst, int bstride, float* fdst,
;                                        float scale) const {
;     ...
;         if (CAT == 2) {
;           unsigned q[8];
; #pragma unroll
;           for (int e = 0; e < 8; ++e) q[e] = (unsigned)(__frcp_rn(1.f + __expf(-v[e])) * 255.f + 0.5f);
;           u32x2 w8;
;           w8[0] = q[0] | (q[1] << 8) | (q[2] << 16) | (q[3] << 24);
;           w8[1] = q[4] | (q[5] << 8) | (q[6] << 16) | (q[7] << 24);
;           *(u32x2*)((unsigned char*)bdst + (size_t)r * 1024 + c0) = w8;
;           continue;
	v_fma_f32 v70, v78, v77, v77
	v_pk_fma_f32 v[70:71], v[70:71], s[2:3], 0.5 op_sel_hi:[1,0,0]
	v_exp_f32_e32 v68, v68
	v_cvt_u32_f32_e32 v76, v71
	v_cvt_u32_f32_e32 v77, v70
	v_pk_add_f32 v[70:71], v[72:73], 1.0 op_sel_hi:[1,0]
	v_exp_f32_e32 v69, v69
	v_rcp_f32_e32 v73, v71
	v_pk_add_f32 v[68:69], v[68:69], 1.0 op_sel_hi:[1,0]
	v_fma_f32 v78, -v71, v73, 1.0
	v_fma_f32 v71, v78, v73, v73
	v_rcp_f32_e32 v73, v70
	s_nop 0
	v_fma_f32 v78, -v70, v73, 1.0
	v_fma_f32 v70, v78, v73, v73
	v_pk_fma_f32 v[70:71], v[70:71], s[2:3], 0.5 op_sel_hi:[1,0,0]
	s_nop 0
	v_cvt_u32_f32_e32 v72, v70
	v_cvt_u32_f32_e32 v73, v71
	v_pk_add_f32 v[70:71], v[74:75], 1.0 op_sel_hi:[1,0]
	v_lshlrev_b32_e32 v72, 8, v72
	v_rcp_f32_e32 v75, v71
	v_lshlrev_b32_e32 v73, 8, v73
	v_or_b32_e32 v73, v73, v76
	v_or_b32_e32 v72, v72, v77
	v_fma_f32 v78, -v71, v75, 1.0
	v_fma_f32 v71, v78, v75, v75
	v_rcp_f32_e32 v75, v70
	s_nop 0
	v_fma_f32 v78, -v70, v75, 1.0
	v_fma_f32 v70, v78, v75, v75
	v_rcp_f32_e32 v75, v69
	v_pk_fma_f32 v[70:71], v[70:71], s[2:3], 0.5 op_sel_hi:[1,0,0]
	v_fma_f32 v78, -v69, v75, 1.0
	v_fma_f32 v69, v78, v75, v75
	v_rcp_f32_e32 v75, v68
	v_cvt_u32_f32_sdwa v70, v70 dst_sel:WORD_1 dst_unused:UNUSED_PAD src0_sel:DWORD
	v_cvt_u32_f32_sdwa v71, v71 dst_sel:WORD_1 dst_unused:UNUSED_PAD src0_sel:DWORD
	v_fma_f32 v78, -v68, v75, 1.0
	v_fma_f32 v68, v78, v75, v75
	v_pk_fma_f32 v[68:69], v[68:69], s[2:3], 0.5 op_sel_hi:[1,0,0]
	v_or_b32_e32 v71, v73, v71
	v_cvt_u32_f32_sdwa v68, v68 dst_sel:BYTE_3 dst_unused:UNUSED_PAD src0_sel:DWORD
	v_cvt_u32_f32_sdwa v69, v69 dst_sel:BYTE_3 dst_unused:UNUSED_PAD src0_sel:DWORD
	v_or_b32_e32 v70, v72, v70
	v_or_b32_e32 v68, v70, v68
	v_or_b32_e32 v69, v71, v69
	v_lshl_add_u64 v[70:71], v[66:67], 0, v[228:229]
	global_store_dwordx2 v[70:71], v[68:69], off
	v_mul_f32_e32 v68, 0xbfb8aa3b, v38
	v_mul_f32_e32 v69, 0xbfb8aa3b, v34
	v_exp_f32_e32 v70, v68
	v_exp_f32_e32 v71, v69
	v_mul_f32_e32 v68, 0xbfb8aa3b, v39
	v_mul_f32_e32 v69, 0xbfb8aa3b, v35
	v_exp_f32_e32 v72, v68
	v_pk_add_f32 v[70:71], v[70:71], 1.0 op_sel_hi:[1,0]
	v_exp_f32_e32 v73, v69
	v_rcp_f32_e32 v77, v71
	v_mul_f32_e32 v68, 0xbfb8aa3b, v40
	v_mul_f32_e32 v69, 0xbfb8aa3b, v36
	v_exp_f32_e32 v74, v68
	v_fma_f32 v78, -v71, v77, 1.0
	v_fma_f32 v71, v78, v77, v77
	v_rcp_f32_e32 v77, v70
	v_exp_f32_e32 v75, v69
	v_mul_f32_e32 v68, 0xbfb8aa3b, v41
	v_mul_f32_e32 v69, 0xbfb8aa3b, v37
	v_fma_f32 v78, -v70, v77, 1.0
	v_fma_f32 v70, v78, v77, v77
	v_pk_fma_f32 v[70:71], v[70:71], s[2:3], 0.5 op_sel_hi:[1,0,0]
	v_exp_f32_e32 v68, v68
	v_cvt_u32_f32_e32 v76, v71
	v_cvt_u32_f32_e32 v77, v70
	v_pk_add_f32 v[70:71], v[72:73], 1.0 op_sel_hi:[1,0]
	v_exp_f32_e32 v69, v69
	v_rcp_f32_e32 v73, v71
	v_pk_add_f32 v[68:69], v[68:69], 1.0 op_sel_hi:[1,0]
	v_fma_f32 v78, -v71, v73, 1.0
	v_fma_f32 v71, v78, v73, v73
	v_rcp_f32_e32 v73, v70
	s_nop 0
	v_fma_f32 v78, -v70, v73, 1.0
	v_fma_f32 v70, v78, v73, v73
	v_pk_fma_f32 v[70:71], v[70:71], s[2:3], 0.5 op_sel_hi:[1,0,0]
	s_nop 0
	v_cvt_u32_f32_e32 v72, v70
	v_cvt_u32_f32_e32 v73, v71
	v_pk_add_f32 v[70:71], v[74:75], 1.0 op_sel_hi:[1,0]
	v_lshlrev_b32_e32 v72, 8, v72
	v_rcp_f32_e32 v75, v71
	v_lshlrev_b32_e32 v73, 8, v73
	v_or_b32_e32 v73, v73, v76
	v_or_b32_e32 v72, v72, v77
	v_fma_f32 v78, -v71, v75, 1.0
	v_fma_f32 v71, v78, v75, v75
	v_rcp_f32_e32 v75, v70
	s_nop 0
	v_fma_f32 v78, -v70, v75, 1.0
	v_fma_f32 v70, v78, v75, v75
	v_rcp_f32_e32 v75, v69
	v_pk_fma_f32 v[70:71], v[70:71], s[2:3], 0.5 op_sel_hi:[1,0,0]
	v_fma_f32 v78, -v69, v75, 1.0
	v_fma_f32 v69, v78, v75, v75
	v_rcp_f32_e32 v75, v68
	v_cvt_u32_f32_sdwa v70, v70 dst_sel:WORD_1 dst_unused:UNUSED_PAD src0_sel:DWORD
	v_cvt_u32_f32_sdwa v71, v71 dst_sel:WORD_1 dst_unused:UNUSED_PAD src0_sel:DWORD
	v_fma_f32 v78, -v68, v75, 1.0
	v_fma_f32 v68, v78, v75, v75
	v_pk_fma_f32 v[68:69], v[68:69], s[2:3], 0.5 op_sel_hi:[1,0,0]
	v_or_b32_e32 v71, v73, v71
	v_cvt_u32_f32_sdwa v68, v68 dst_sel:BYTE_3 dst_unused:UNUSED_PAD src0_sel:DWORD
	v_cvt_u32_f32_sdwa v69, v69 dst_sel:BYTE_3 dst_unused:UNUSED_PAD src0_sel:DWORD
	v_or_b32_e32 v70, v72, v70
	v_or_b32_e32 v68, v70, v68
	v_or_b32_e32 v69, v71, v69
	v_lshl_add_u64 v[70:71], v[66:67], 0, v[242:243]
	global_store_dwordx2 v[70:71], v[68:69], off
	v_mul_f32_e32 v68, 0xbfb8aa3b, v30
	v_mul_f32_e32 v69, 0xbfb8aa3b, v26
	v_exp_f32_e32 v70, v68
	v_exp_f32_e32 v71, v69
	v_mul_f32_e32 v68, 0xbfb8aa3b, v31
	v_mul_f32_e32 v69, 0xbfb8aa3b, v27
	v_exp_f32_e32 v72, v68
	v_pk_add_f32 v[70:71], v[70:71], 1.0 op_sel_hi:[1,0]
	v_exp_f32_e32 v73, v69
	v_rcp_f32_e32 v77, v71
	v_mul_f32_e32 v68, 0xbfb8aa3b, v32
	v_mul_f32_e32 v69, 0xbfb8aa3b, v28
	v_exp_f32_e32 v74, v68
	v_fma_f32 v78, -v71, v77, 1.0
	v_fma_f32 v71, v78, v77, v77
	v_rcp_f32_e32 v77, v70
	v_exp_f32_e32 v75, v69
	v_mul_f32_e32 v68, 0xbfb8aa3b, v33
	v_mul_f32_e32 v69, 0xbfb8aa3b, v29
	v_fma_f32 v78, -v70, v77, 1.0
	v_fma_f32 v70, v78, v77, v77
	v_pk_fma_f32 v[70:71], v[70:71], s[2:3], 0.5 op_sel_hi:[1,0,0]
	v_exp_f32_e32 v68, v68
	v_cvt_u32_f32_e32 v76, v71
	v_cvt_u32_f32_e32 v77, v70
	v_pk_add_f32 v[70:71], v[72:73], 1.0 op_sel_hi:[1,0]
	v_exp_f32_e32 v69, v69
	v_rcp_f32_e32 v73, v71
	v_pk_add_f32 v[68:69], v[68:69], 1.0 op_sel_hi:[1,0]
	v_fma_f32 v78, -v71, v73, 1.0
	v_fma_f32 v71, v78, v73, v73
	v_rcp_f32_e32 v73, v70
	s_nop 0
	v_fma_f32 v78, -v70, v73, 1.0
	v_fma_f32 v70, v78, v73, v73
	v_pk_fma_f32 v[70:71], v[70:71], s[2:3], 0.5 op_sel_hi:[1,0,0]
	s_nop 0
	v_cvt_u32_f32_e32 v72, v70
	v_cvt_u32_f32_e32 v73, v71
	v_pk_add_f32 v[70:71], v[74:75], 1.0 op_sel_hi:[1,0]
	v_lshlrev_b32_e32 v72, 8, v72
	v_rcp_f32_e32 v75, v71
	v_lshlrev_b32_e32 v73, 8, v73
	v_or_b32_e32 v73, v73, v76
	v_or_b32_e32 v72, v72, v77
;   template <int CAT>
;   __device__ __forceinline__ void slot(const f32x4 (&acc)[2][2][4][2], int bj, int r00, int p0, bool sunit, int fq, int c0, bf16_t* bdst, int bstride, float* fdst,
;                                        float scale) const {
;     ...
;         if (CAT == 2) {
;           unsigned q[8];
; #pragma unroll
;           for (int e = 0; e < 8; ++e) q[e] = (unsigned)(__frcp_rn(1.f + __expf(-v[e])) * 255.f + 0.5f);
;           u32x2 w8;
;           w8[0] = q[0] | (q[1] << 8) | (q[2] << 16) | (q[3] << 24);
;           w8[1] = q[4] | (q[5] << 8) | (q[6] << 16) | (q[7] << 24);
;           *(u32x2*)((unsigned char*)bdst + (size_t)r * 1024 + c0) = w8;
;           continue;
	v_fma_f32 v78, -v71, v75, 1.0
	v_fma_f32 v71, v78, v75, v75
	v_rcp_f32_e32 v75, v70
	s_nop 0
	v_fma_f32 v78, -v70, v75, 1.0
	v_fma_f32 v70, v78, v75, v75
	v_rcp_f32_e32 v75, v69
	v_pk_fma_f32 v[70:71], v[70:71], s[2:3], 0.5 op_sel_hi:[1,0,0]
	v_fma_f32 v78, -v69, v75, 1.0
	v_fma_f32 v69, v78, v75, v75
	v_rcp_f32_e32 v75, v68
	v_cvt_u32_f32_sdwa v70, v70 dst_sel:WORD_1 dst_unused:UNUSED_PAD src0_sel:DWORD
	v_cvt_u32_f32_sdwa v71, v71 dst_sel:WORD_1 dst_unused:UNUSED_PAD src0_sel:DWORD
	v_fma_f32 v78, -v68, v75, 1.0
	v_fma_f32 v68, v78, v75, v75
	v_pk_fma_f32 v[68:69], v[68:69], s[2:3], 0.5 op_sel_hi:[1,0,0]
	v_or_b32_e32 v71, v73, v71
	v_cvt_u32_f32_sdwa v68, v68 dst_sel:BYTE_3 dst_unused:UNUSED_PAD src0_sel:DWORD
	v_cvt_u32_f32_sdwa v69, v69 dst_sel:BYTE_3 dst_unused:UNUSED_PAD src0_sel:DWORD
	v_or_b32_e32 v70, v72, v70
	v_or_b32_e32 v68, v70, v68
	v_or_b32_e32 v69, v71, v69
	v_lshl_add_u64 v[70:71], v[66:67], 0, v[224:225]
	global_store_dwordx2 v[70:71], v[68:69], off
	v_mul_f32_e32 v68, 0xbfb8aa3b, v22
	v_mul_f32_e32 v69, 0xbfb8aa3b, v18
	v_exp_f32_e32 v70, v68
	v_exp_f32_e32 v71, v69
	v_mul_f32_e32 v68, 0xbfb8aa3b, v23
	v_mul_f32_e32 v69, 0xbfb8aa3b, v19
	v_exp_f32_e32 v72, v68
	v_pk_add_f32 v[70:71], v[70:71], 1.0 op_sel_hi:[1,0]
	v_exp_f32_e32 v73, v69
	v_rcp_f32_e32 v77, v71
	v_mul_f32_e32 v68, 0xbfb8aa3b, v24
	v_mul_f32_e32 v69, 0xbfb8aa3b, v20
	v_exp_f32_e32 v74, v68
	v_fma_f32 v78, -v71, v77, 1.0
	v_fma_f32 v71, v78, v77, v77
	v_rcp_f32_e32 v77, v70
	v_exp_f32_e32 v75, v69
	v_mul_f32_e32 v68, 0xbfb8aa3b, v25
	v_mul_f32_e32 v69, 0xbfb8aa3b, v21
	v_fma_f32 v78, -v70, v77, 1.0
	v_fma_f32 v70, v78, v77, v77
	v_pk_fma_f32 v[70:71], v[70:71], s[2:3], 0.5 op_sel_hi:[1,0,0]
	v_exp_f32_e32 v68, v68
	v_cvt_u32_f32_e32 v76, v71
	v_cvt_u32_f32_e32 v77, v70
	v_pk_add_f32 v[70:71], v[72:73], 1.0 op_sel_hi:[1,0]
	v_exp_f32_e32 v69, v69
	v_rcp_f32_e32 v73, v71
	v_pk_add_f32 v[68:69], v[68:69], 1.0 op_sel_hi:[1,0]
	v_fma_f32 v78, -v71, v73, 1.0
	v_fma_f32 v71, v78, v73, v73
	v_rcp_f32_e32 v73, v70
	s_nop 0
	v_fma_f32 v78, -v70, v73, 1.0
	v_fma_f32 v70, v78, v73, v73
	v_pk_fma_f32 v[70:71], v[70:71], s[2:3], 0.5 op_sel_hi:[1,0,0]
	s_nop 0
	v_cvt_u32_f32_e32 v72, v70
	v_cvt_u32_f32_e32 v73, v71
	v_pk_add_f32 v[70:71], v[74:75], 1.0 op_sel_hi:[1,0]
	v_lshlrev_b32_e32 v72, 8, v72
	v_rcp_f32_e32 v75, v71
	v_lshlrev_b32_e32 v73, 8, v73
	v_or_b32_e32 v73, v73, v76
	v_or_b32_e32 v72, v72, v77
	v_fma_f32 v78, -v71, v75, 1.0
	v_fma_f32 v71, v78, v75, v75
	v_rcp_f32_e32 v75, v70
	s_nop 0
	v_fma_f32 v78, -v70, v75, 1.0
	v_fma_f32 v70, v78, v75, v75
	v_rcp_f32_e32 v75, v69
	v_pk_fma_f32 v[70:71], v[70:71], s[2:3], 0.5 op_sel_hi:[1,0,0]
	v_fma_f32 v78, -v69, v75, 1.0
	v_fma_f32 v69, v78, v75, v75
	v_rcp_f32_e32 v75, v68
	v_cvt_u32_f32_sdwa v70, v70 dst_sel:WORD_1 dst_unused:UNUSED_PAD src0_sel:DWORD
	v_cvt_u32_f32_sdwa v71, v71 dst_sel:WORD_1 dst_unused:UNUSED_PAD src0_sel:DWORD
	v_fma_f32 v78, -v68, v75, 1.0
	v_fma_f32 v68, v78, v75, v75
	v_pk_fma_f32 v[68:69], v[68:69], s[2:3], 0.5 op_sel_hi:[1,0,0]
	v_or_b32_e32 v71, v73, v71
	v_cvt_u32_f32_sdwa v68, v68 dst_sel:BYTE_3 dst_unused:UNUSED_PAD src0_sel:DWORD
	v_cvt_u32_f32_sdwa v69, v69 dst_sel:BYTE_3 dst_unused:UNUSED_PAD src0_sel:DWORD
	v_or_b32_e32 v70, v72, v70
	v_or_b32_e32 v68, v70, v68
	v_or_b32_e32 v69, v71, v69
	v_lshl_add_u64 v[70:71], v[66:67], 0, v[222:223]
	global_store_dwordx2 v[70:71], v[68:69], off
	v_mul_f32_e32 v68, 0xbfb8aa3b, v12
	v_mul_f32_e32 v69, 0xbfb8aa3b, v8
	v_exp_f32_e32 v70, v68
	v_exp_f32_e32 v71, v69
	v_mul_f32_e32 v68, 0xbfb8aa3b, v13
	v_mul_f32_e32 v69, 0xbfb8aa3b, v9
	v_exp_f32_e32 v72, v68
	v_pk_add_f32 v[70:71], v[70:71], 1.0 op_sel_hi:[1,0]
	v_exp_f32_e32 v73, v69
	v_rcp_f32_e32 v77, v71
	v_mul_f32_e32 v68, 0xbfb8aa3b, v14
	v_mul_f32_e32 v69, 0xbfb8aa3b, v10
	v_exp_f32_e32 v74, v68
	v_fma_f32 v78, -v71, v77, 1.0
	v_fma_f32 v71, v78, v77, v77
	v_rcp_f32_e32 v77, v70
	v_exp_f32_e32 v75, v69
	v_mul_f32_e32 v68, 0xbfb8aa3b, v15
	v_mul_f32_e32 v69, 0xbfb8aa3b, v11
	v_fma_f32 v78, -v70, v77, 1.0
	v_fma_f32 v70, v78, v77, v77
	v_pk_fma_f32 v[70:71], v[70:71], s[2:3], 0.5 op_sel_hi:[1,0,0]
;   template <int CAT>
;   __device__ __forceinline__ void slot(const f32x4 (&acc)[2][2][4][2], int bj, int r00, int p0, bool sunit, int fq, int c0, bf16_t* bdst, int bstride, float* fdst,
;                                        float scale) const {
;     ...
;         if (CAT == 2) {
;           unsigned q[8];
; #pragma unroll
;           for (int e = 0; e < 8; ++e) q[e] = (unsigned)(__frcp_rn(1.f + __expf(-v[e])) * 255.f + 0.5f);
;           u32x2 w8;
;           w8[0] = q[0] | (q[1] << 8) | (q[2] << 16) | (q[3] << 24);
;           w8[1] = q[4] | (q[5] << 8) | (q[6] << 16) | (q[7] << 24);
;           *(u32x2*)((unsigned char*)bdst + (size_t)r * 1024 + c0) = w8;
;           continue;
	v_exp_f32_e32 v68, v68
	v_cvt_u32_f32_e32 v76, v71
	v_cvt_u32_f32_e32 v77, v70
	v_pk_add_f32 v[70:71], v[72:73], 1.0 op_sel_hi:[1,0]
	v_exp_f32_e32 v69, v69
	v_rcp_f32_e32 v73, v71
	v_pk_add_f32 v[68:69], v[68:69], 1.0 op_sel_hi:[1,0]
	v_fma_f32 v78, -v71, v73, 1.0
	v_fma_f32 v71, v78, v73, v73
	v_rcp_f32_e32 v73, v70
	s_nop 0
	v_fma_f32 v78, -v70, v73, 1.0
	v_fma_f32 v70, v78, v73, v73
	v_pk_fma_f32 v[70:71], v[70:71], s[2:3], 0.5 op_sel_hi:[1,0,0]
	s_nop 0
	v_cvt_u32_f32_e32 v72, v70
	v_cvt_u32_f32_e32 v73, v71
	v_pk_add_f32 v[70:71], v[74:75], 1.0 op_sel_hi:[1,0]
	v_lshlrev_b32_e32 v72, 8, v72
	v_rcp_f32_e32 v75, v71
	v_lshlrev_b32_e32 v73, 8, v73
	v_or_b32_e32 v73, v73, v76
	v_or_b32_e32 v72, v72, v77
	v_fma_f32 v78, -v71, v75, 1.0
	v_fma_f32 v71, v78, v75, v75
	v_rcp_f32_e32 v75, v70
	s_nop 0
	v_fma_f32 v78, -v70, v75, 1.0
	v_fma_f32 v70, v78, v75, v75
	v_rcp_f32_e32 v75, v69
	v_pk_fma_f32 v[70:71], v[70:71], s[2:3], 0.5 op_sel_hi:[1,0,0]
	v_fma_f32 v78, -v69, v75, 1.0
	v_fma_f32 v69, v78, v75, v75
	v_rcp_f32_e32 v75, v68
	v_cvt_u32_f32_sdwa v70, v70 dst_sel:WORD_1 dst_unused:UNUSED_PAD src0_sel:DWORD
	v_cvt_u32_f32_sdwa v71, v71 dst_sel:WORD_1 dst_unused:UNUSED_PAD src0_sel:DWORD
	v_fma_f32 v78, -v68, v75, 1.0
	v_fma_f32 v68, v78, v75, v75
	v_pk_fma_f32 v[68:69], v[68:69], s[2:3], 0.5 op_sel_hi:[1,0,0]
	v_or_b32_e32 v71, v73, v71
	v_cvt_u32_f32_sdwa v68, v68 dst_sel:BYTE_3 dst_unused:UNUSED_PAD src0_sel:DWORD
	v_cvt_u32_f32_sdwa v69, v69 dst_sel:BYTE_3 dst_unused:UNUSED_PAD src0_sel:DWORD
	v_or_b32_e32 v70, v72, v70
	v_or_b32_e32 v68, v70, v68
	v_or_b32_e32 v69, v71, v69
	v_lshl_add_u64 v[70:71], v[66:67], 0, v[148:149]
	global_store_dwordx2 v[70:71], v[68:69], off
	v_mul_f32_e32 v68, 0xbfb8aa3b, v4
	v_mul_f32_e32 v69, 0xbfb8aa3b, v0
	v_exp_f32_e32 v70, v68
	v_exp_f32_e32 v71, v69
	v_mul_f32_e32 v68, 0xbfb8aa3b, v5
	v_mul_f32_e32 v69, 0xbfb8aa3b, v1
	v_exp_f32_e32 v72, v68
	v_pk_add_f32 v[70:71], v[70:71], 1.0 op_sel_hi:[1,0]
	v_exp_f32_e32 v73, v69
	v_rcp_f32_e32 v77, v71
	v_mul_f32_e32 v68, 0xbfb8aa3b, v6
	v_mul_f32_e32 v69, 0xbfb8aa3b, v2
	v_exp_f32_e32 v74, v68
	v_fma_f32 v78, -v71, v77, 1.0
	v_fma_f32 v71, v78, v77, v77
	v_rcp_f32_e32 v77, v70
	v_exp_f32_e32 v75, v69
	v_mul_f32_e32 v68, 0xbfb8aa3b, v7
	v_mul_f32_e32 v69, 0xbfb8aa3b, v3
	v_fma_f32 v78, -v70, v77, 1.0
	v_fma_f32 v70, v78, v77, v77
	v_pk_fma_f32 v[70:71], v[70:71], s[2:3], 0.5 op_sel_hi:[1,0,0]
	v_exp_f32_e32 v68, v68
	v_cvt_u32_f32_e32 v76, v71
	v_cvt_u32_f32_e32 v77, v70
	v_pk_add_f32 v[70:71], v[72:73], 1.0 op_sel_hi:[1,0]
	v_exp_f32_e32 v69, v69
	v_rcp_f32_e32 v73, v71
	v_pk_add_f32 v[68:69], v[68:69], 1.0 op_sel_hi:[1,0]
	v_lshl_add_u64 v[66:67], v[66:67], 0, v[146:147]
	v_fma_f32 v78, -v71, v73, 1.0
	v_fma_f32 v71, v78, v73, v73
	v_rcp_f32_e32 v73, v70
	s_nop 0
	v_fma_f32 v78, -v70, v73, 1.0
	v_fma_f32 v70, v78, v73, v73
	v_pk_fma_f32 v[70:71], v[70:71], s[2:3], 0.5 op_sel_hi:[1,0,0]
	s_nop 0
	v_cvt_u32_f32_e32 v72, v70
	v_cvt_u32_f32_e32 v73, v71
	v_pk_add_f32 v[70:71], v[74:75], 1.0 op_sel_hi:[1,0]
	v_lshlrev_b32_e32 v72, 8, v72
	v_rcp_f32_e32 v75, v71
	v_lshlrev_b32_e32 v73, 8, v73
	v_or_b32_e32 v73, v73, v76
	v_or_b32_e32 v72, v72, v77
	v_fma_f32 v78, -v71, v75, 1.0
	v_fma_f32 v71, v78, v75, v75
	v_rcp_f32_e32 v75, v70
	s_nop 0
	v_fma_f32 v78, -v70, v75, 1.0
	v_fma_f32 v70, v78, v75, v75
	v_rcp_f32_e32 v75, v69
	v_pk_fma_f32 v[70:71], v[70:71], s[2:3], 0.5 op_sel_hi:[1,0,0]
	v_fma_f32 v78, -v69, v75, 1.0
	v_fma_f32 v69, v78, v75, v75
	v_rcp_f32_e32 v75, v68
	v_cvt_u32_f32_sdwa v70, v70 dst_sel:WORD_1 dst_unused:UNUSED_PAD src0_sel:DWORD
	v_cvt_u32_f32_sdwa v71, v71 dst_sel:WORD_1 dst_unused:UNUSED_PAD src0_sel:DWORD
	v_fma_f32 v78, -v68, v75, 1.0
	v_fma_f32 v68, v78, v75, v75
	v_pk_fma_f32 v[68:69], v[68:69], s[2:3], 0.5 op_sel_hi:[1,0,0]
	v_or_b32_e32 v71, v73, v71
	v_cvt_u32_f32_sdwa v68, v68 dst_sel:BYTE_3 dst_unused:UNUSED_PAD src0_sel:DWORD
	v_cvt_u32_f32_sdwa v69, v69 dst_sel:BYTE_3 dst_unused:UNUSED_PAD src0_sel:DWORD
	v_or_b32_e32 v70, v72, v70
	v_or_b32_e32 v68, v70, v68
	v_or_b32_e32 v69, v71, v69
	global_store_dwordx2 v[66:67], v[68:69], off
